# attention task index remapped so batch b runs on XCD b (bx%8) and adjacent 256-row blocks run concurrently on the same XCD (K/V halo L2 hits), all 3 attention phases; on top of v022
# baseline (speedup 1.0000x reference)
.LBB0_446:
	s_or_b64 exec, exec, s[0:1]
	s_add_u32 s8, s40, 0xf000000
	s_addc_u32 s9, s41, 0
	s_add_u32 s10, s40, 0x13000000
	s_waitcnt lgkmcnt(0)
	v_mov_b32_e32 v0, v180
	s_addc_u32 s11, s41, 0
	v_mov_b32_e32 v4, v182
	s_barrier
	s_cmpk_gt_i32 s2, 0xfff
	v_readfirstlane_b32 s5, v4
	s_cbranch_scc1 .LBB0_463
	s_bfe_u32 s99, s2, 0x50003
	s_and_b32 s0, s2, 7
	s_lshl_b32 s0, s0, 8
	s_or_b32 s99, s99, s0
	s_bfe_u32 s0, s2, 0x30008
	s_lshl_b32 s0, s0, 5
	s_or_b32 s99, s99, s0
	s_and_b32 s0, s2, 0x800
	s_or_b32 s99, s99, s0
	s_and_b32 s0, s99, 0x7ff
	s_cmpk_lt_u32 s2, 0x800
	s_cselect_b32 s60, 16, 4
	s_cselect_b32 s1, 0, 3
	s_cselect_b32 s6, 0, 2
	s_cselect_b32 s4, 4, 2
	s_and_b32 s7, s1, s99
	s_lshr_b32 s0, s0, s6
	s_add_i32 s1, s60, -1
	s_and_b32 s61, s0, s1
	s_lshr_b32 s0, s0, s4
	s_and_b32 s63, s0, 15
	s_lshr_b32 s16, s0, 4
	s_lshl_b32 s0, s16, 18
	s_lshl_b32 s1, s63, 21
	s_add_i32 s1, s1, s0
	s_lshl_b32 s95, s7, 8
	s_lshl_b32 s6, s1, 1
	s_add_u32 s36, s8, s6
	s_addc_u32 s37, s9, 0
	s_add_u32 s44, s10, s6
	v_lshrrev_b32_e32 v160, 3, v4
	v_lshlrev_b32_e32 v1, 4, v4
	s_addc_u32 s45, s11, 0
	v_lshlrev_b32_e32 v0, s4, v160
	v_and_b32_e32 v161, 0x70, v1
	v_lshl_or_b32 v80, v0, 7, v161
	s_cmp_lg_u32 s7, 0
	v_mov_b32_e32 v81, 0
	s_cselect_b64 s[0:1], -1, 0
	s_cmp_eq_u32 s7, 0
	v_lshl_add_u64 v[0:1], s[36:37], 0, v[80:81]
	v_lshl_add_u64 v[2:3], s[44:45], 0, v[80:81]
	s_cbranch_scc1 .LBB0_450
	s_add_i32 s36, s95, 0xffffff80
	s_ashr_i32 s37, s36, 31
	s_lshl_b64 s[36:37], s[36:37], s4
	s_add_u32 s36, s36, s61
	s_addc_u32 s37, s37, 0
	s_lshl_b64 s[36:37], s[36:37], 7
	v_lshl_add_u64 v[6:7], v[0:1], 0, s[36:37]
	v_lshl_add_u64 v[8:9], v[2:3], 0, s[36:37]
	global_load_dwordx4 v[84:87], v[6:7], off nt
	global_load_dwordx4 v[80:83], v[8:9], off nt
	s_andn2_b64 vcc, exec, s[0:1]
	s_mov_b32 s17, 0
	s_cbranch_vccnz .LBB0_451

.LBB0_454:
	s_add_i32 s0, s63, 1
	v_cvt_f32_u32_e32 v4, s0
	v_add_u32_e32 v0, v164, v171
	s_waitcnt vmcnt(13)
	ds_write_b128 v0, v[84:87]
	s_waitcnt vmcnt(12)
	ds_write_b128 v0, v[80:83] offset:55296
	ds_write_b128 v0, v[96:99] offset:9216
	ds_write_b128 v0, v[92:95] offset:64512
	s_waitcnt vmcnt(4)
	ds_write_b128 v0, v[104:107] offset:18432
	ds_write_b128 v174, v[100:103] offset:18432
	ds_write_b128 v0, v[120:123] offset:27648
	ds_write_b128 v174, v[112:115] offset:27648
	ds_write_b128 v0, v[124:127] offset:36864
	ds_write_b128 v174, v[108:111] offset:36864
	ds_write_b128 v0, v[128:131] offset:46080
	ds_write_b128 v174, v[116:119] offset:46080
	ds_write_b128 v185, v[136:139]
	s_mov_b32 s0, 0xc2fc0000
	v_mul_f32_e32 v0, -0.5, v4
	v_cmp_gt_f32_e64 s[6:7], s0, v0
	s_and_b64 s[0:1], s[6:7], exec
	s_cselect_b32 s96, 0xffffffc0, 0
	s_add_i32 s88, s42, s88
	s_cmpk_gt_i32 s88, 0xfff
	s_cselect_b64 s[58:59], -1, 0
	s_and_b64 vcc, exec, s[58:59]
	s_mov_b32 s93, s16
	ds_write_b128 v185, v[132:135] offset:1152
	ds_write_b128 v185, v[144:147] offset:2304
	ds_write_b128 v185, v[140:143] offset:3456
	s_cbranch_vccnz .LBB0_461
	s_bfe_u32 s99, s88, 0x50003
	s_and_b32 s0, s88, 7
	s_lshl_b32 s0, s0, 8
	s_or_b32 s99, s99, s0
	s_bfe_u32 s0, s88, 0x30008
	s_lshl_b32 s0, s0, 5
	s_or_b32 s99, s99, s0
	s_and_b32 s0, s88, 0x800
	s_or_b32 s99, s99, s0
	s_and_b32 s0, s99, 0x7ff
	s_cmpk_lt_u32 s88, 0x800
	s_cselect_b32 s89, 16, 4
	s_cselect_b32 s1, 0, 3
	s_cselect_b32 s18, 0, 2
	s_cselect_b32 s94, 4, 2
	s_and_b32 s79, s1, s99
	s_lshr_b32 s0, s0, s18
	s_add_i32 s1, s89, -1
	s_and_b32 s90, s0, s1
	s_lshr_b32 s0, s0, s94
	s_and_b32 s92, s0, 15
	s_lshr_b32 s93, s0, 4
	s_lshl_b32 s0, s93, 18
	s_lshl_b32 s1, s92, 21
	s_add_i32 s1, s1, s0
	s_lshl_b32 s91, s79, 8
	s_lshl_b32 s97, s1, 1
	s_add_u32 vcc_lo, s8, s97
	s_addc_u32 vcc_hi, s9, 0
	s_add_u32 s18, s10, s97
	s_addc_u32 s19, s11, 0
	v_lshlrev_b32_e32 v0, s94, v160
	v_lshl_or_b32 v88, v0, 7, v161
	s_cmp_lg_u32 s79, 0
	s_cselect_b64 s[0:1], -1, 0
	s_cmp_eq_u32 s79, 0
	v_lshl_add_u64 v[0:1], vcc, 0, v[88:89]
	v_lshl_add_u64 v[2:3], s[18:19], 0, v[88:89]
	s_cbranch_scc1 .LBB0_458
	s_add_i32 s18, s91, 0xffffff80
	s_ashr_i32 s19, s18, 31
	s_lshl_b64 s[18:19], s[18:19], s94
	s_add_u32 s18, s18, s90
	s_addc_u32 s19, s19, 0
	s_lshl_b64 s[18:19], s[18:19], 7
	v_lshl_add_u64 v[6:7], v[0:1], 0, s[18:19]
	v_lshl_add_u64 v[8:9], v[2:3], 0, s[18:19]
	global_load_dwordx4 v[84:87], v[6:7], off nt
	global_load_dwordx4 v[80:83], v[8:9], off nt
	s_andn2_b64 vcc, exec, s[0:1]
	s_cbranch_vccnz .LBB0_459

.LBB0_515:
	s_or_b64 exec, exec, s[0:1]
	s_waitcnt lgkmcnt(0)
	v_mov_b32_e32 v0, v180
	v_mov_b32_e32 v6, v182
	s_barrier
	s_cmpk_gt_i32 s2, 0x7ff
	v_readfirstlane_b32 s16, v6
	s_cbranch_scc1 .LBB0_532
	s_bfe_u32 s99, s2, 0x50003
	s_and_b32 s0, s2, 7
	s_lshl_b32 s0, s0, 8
	s_or_b32 s99, s99, s0
	s_lshr_b32 s0, s2, 8
	s_lshl_b32 s0, s0, 5
	s_or_b32 s99, s99, s0
	s_lshl_b32 s0, s99, 8
	s_and_b32 s63, s0, 0xf00
	s_ashr_i32 s0, s99, 8
	s_bfe_u32 s62, s99, 0x40004
	s_ashr_i32 s1, s0, 31
	s_lshl_b64 s[4:5], s[0:1], 18
	s_lshl_b32 s1, s62, 21
	s_add_u32 s4, s4, s1
	s_addc_u32 s5, s5, 0
	s_lshl_b64 s[4:5], s[4:5], 1
	s_add_u32 s18, s8, s4
	s_addc_u32 s19, s9, s5
	s_add_u32 s36, s10, s4
	s_addc_u32 s37, s11, s5
	v_lshlrev_b32_e32 v0, 4, v6
	s_cmp_lg_u32 s63, 0
	v_mov_b32_e32 v1, 0
	s_cselect_b64 s[6:7], -1, 0
	s_cmp_eq_u32 s63, 0
	v_lshl_add_u64 v[2:3], s[18:19], 0, v[0:1]
	v_lshl_add_u64 v[4:5], s[36:37], 0, v[0:1]
	s_cbranch_scc1 .LBB0_519
	s_lshl_b32 s1, s63, 7
	s_add_u32 s18, s1, 0xffffc000
	s_addc_u32 s19, 0, -1
	v_lshl_add_u64 v[8:9], v[2:3], 0, s[18:19]
	v_lshl_add_u64 v[10:11], v[4:5], 0, s[18:19]
	global_load_dwordx4 v[84:87], v[8:9], off nt
	global_load_dwordx4 v[80:83], v[10:11], off nt
	s_andn2_b64 vcc, exec, s[6:7]
	s_mov_b32 s17, 0
	s_cbranch_vccnz .LBB0_520

.LBB0_523:
	s_add_i32 s1, s62, 1
	v_cvt_f32_u32_e32 v4, s1
	v_add_u32_e32 v0, v204, v210
	s_waitcnt vmcnt(13)
	ds_write_b128 v0, v[84:87]
	s_waitcnt vmcnt(12)
	ds_write_b128 v0, v[80:83] offset:55296
	ds_write_b128 v0, v[96:99] offset:9216
	ds_write_b128 v0, v[92:95] offset:64512
	s_waitcnt vmcnt(4)
	ds_write_b128 v0, v[128:131] offset:18432
	ds_write_b128 v213, v[124:127] offset:55296
	ds_write_b128 v0, v[120:123] offset:27648
	ds_write_b128 v214, v[116:119] offset:55296
	ds_write_b128 v0, v[112:115] offset:36864
	ds_write_b128 v215, v[108:111] offset:55296
	ds_write_b128 v0, v[104:107] offset:46080
	ds_write_b128 v216, v[100:103] offset:55296
	ds_write_b128 v224, v[140:143]
	s_mov_b32 s54, s0
	v_mul_f32_e32 v0, -0.5, v4
	v_cmp_gt_f32_e64 s[6:7], s69, v0
	s_and_b64 s[18:19], s[6:7], exec
	s_cselect_b32 s1, 0xffffffc0, 0
	s_add_i32 s95, s42, s95
	s_cmpk_gt_i32 s95, 0x7ff
	s_cselect_b64 s[56:57], -1, 0
	s_and_b64 vcc, exec, s[56:57]
	ds_write_b128 v224, v[144:147] offset:1152
	ds_write_b128 v224, v[132:135] offset:2304
	ds_write_b128 v224, v[136:139] offset:3456
	s_cbranch_vccnz .LBB0_530
	s_bfe_u32 s99, s95, 0x50003
	s_and_b32 s54, s95, 7
	s_lshl_b32 s54, s54, 8
	s_or_b32 s99, s99, s54
	s_lshr_b32 s54, s95, 8
	s_lshl_b32 s54, s54, 5
	s_or_b32 s99, s99, s54
	s_ashr_i32 s54, s99, 8
	s_bfe_u32 s97, s99, 0x40004
	s_ashr_i32 s55, s54, 31
	s_lshl_b32 s96, s99, 8
	s_and_b32 s96, s96, 0xf00
	s_lshl_b64 s[18:19], s[54:55], 18
	s_lshl_b32 s16, s97, 21
	s_add_u32 s58, s18, s16
	s_addc_u32 s59, s19, 0
	s_cmp_lg_u32 s96, 0
	s_cselect_b64 s[60:61], -1, 0
	s_lshl_b64 s[18:19], s[58:59], 1
	s_cmp_eq_u32 s96, 0
	v_lshl_add_u64 v[0:1], v[184:185], 0, s[18:19]
	v_lshl_add_u64 v[2:3], v[186:187], 0, s[18:19]
	s_cbranch_scc1 .LBB0_527
	s_lshl_b32 s16, s96, 7
	s_add_u32 s18, s16, 0xffffc000
	s_addc_u32 s19, 0, -1
	v_lshl_add_u64 v[6:7], v[0:1], 0, s[18:19]
	v_lshl_add_u64 v[8:9], v[2:3], 0, s[18:19]
	global_load_dwordx4 v[84:87], v[6:7], off nt
	global_load_dwordx4 v[80:83], v[8:9], off nt
	s_andn2_b64 vcc, exec, s[60:61]
	s_cbranch_vccnz .LBB0_528

.LBB0_1221:
	s_or_b64 exec, exec, s[0:1]
	s_waitcnt lgkmcnt(0)
	v_mov_b32_e32 v0, v180
	v_mov_b32_e32 v6, v182
	s_barrier
	s_and_b64 vcc, exec, s[6:7]
	v_readfirstlane_b32 s18, v6
	s_cbranch_vccnz .LBB0_1242
	s_add_u32 s10, s40, 0x6000000
	s_addc_u32 s11, s41, 0
	s_bfe_u32 s99, s2, 0x50003
	s_and_b32 s0, s2, 7
	s_lshl_b32 s0, s0, 6
	s_or_b32 s99, s99, s0
	s_lshr_b32 s0, s2, 8
	s_lshl_b32 s0, s0, 5
	s_or_b32 s99, s99, s0
	s_lshl_b32 s0, s99, 8
	s_and_b32 s88, s0, 0xf00
	s_lshr_b32 s0, s99, 2
	s_ashr_i32 s16, s99, 6
	s_and_b32 s0, s0, 12
	s_ashr_i32 s17, s16, 31
	s_lshl_b32 s1, s0, 19
	s_lshl_b64 s[12:13], s[16:17], 18
	s_add_u32 s12, s12, s1
	s_addc_u32 s13, s13, 0
	s_lshl_b64 s[12:13], s[12:13], 1
	s_add_u32 s36, s30, s12
	s_addc_u32 s37, s31, s13
	s_add_u32 s44, s10, s12
	s_addc_u32 s45, s11, s13
	v_lshlrev_b32_e32 v0, 4, v6
	s_cmp_lg_u32 s88, 0
	v_mov_b32_e32 v1, 0
	s_cselect_b64 s[12:13], -1, 0
	s_cmp_eq_u32 s88, 0
	v_lshl_add_u64 v[4:5], s[36:37], 0, v[0:1]
	v_lshl_add_u64 v[2:3], s[44:45], 0, v[0:1]
	s_cbranch_scc1 .LBB0_1225
	s_lshl_b32 s1, s88, 7
	s_add_u32 s36, s1, 0xffffc000
	s_addc_u32 s37, 0, -1
	v_lshl_add_u64 v[8:9], v[4:5], 0, s[36:37]
	v_lshl_add_u64 v[10:11], v[2:3], 0, s[36:37]
	global_load_dwordx4 v[84:87], v[8:9], off nt
	global_load_dwordx4 v[80:83], v[10:11], off nt
	s_mov_b32 s1, 0
	s_andn2_b64 vcc, exec, s[12:13]
	s_mov_b32 s62, 1
	s_cbranch_vccnz .LBB0_1226

.LBB0_1231:
	s_add_i32 s12, s0, 1
	v_cvt_f32_u32_e32 v4, s12
	v_mul_f32_e32 v0, -0.5, v4
	v_cmp_gt_f32_e64 s[12:13], s66, v0
	s_and_b64 s[54:55], s[12:13], exec
	s_cselect_b32 s17, 0xffffffc0, 0
	s_lshl_b64 s[54:55], s[0:1], 2
	s_add_u32 s54, s50, s54
	s_addc_u32 s55, s51, s55
	s_load_dword s98, s[54:55], 0x0
	s_lshr_b32 s54, s62, 2
	s_mul_i32 s54, s54, s42
	s_add_i32 s56, s54, s2
	s_cmpk_gt_i32 s56, 0x1ff
	s_cselect_b64 s[58:59], -1, 0
	s_and_b32 s57, s62, 3
	s_cmp_eq_u32 s57, 0
	s_cselect_b64 s[54:55], -1, 0
	s_bfe_u32 s99, s56, 0x50003
	s_and_b32 s60, s56, 7
	s_lshl_b32 s60, s60, 6
	s_or_b32 s99, s99, s60
	s_lshr_b32 s60, s56, 8
	s_lshl_b32 s60, s60, 5
	s_or_b32 s56, s99, s60
	s_lshl_b32 s60, s56, 8
	s_and_b32 s86, s60, 0xf00
	s_lshr_b32 s60, s56, 2
	s_and_b32 s60, s60, 12
	s_or_b32 s87, s60, s57
	s_ashr_i32 s56, s56, 6
	s_and_b64 vcc, exec, s[58:59]
	s_waitcnt vmcnt(4)
	ds_write_b128 v189, v[134:137]
	ds_write_b128 v189, v[130:133] offset:1152
	ds_write_b128 v189, v[142:145] offset:2304
	ds_write_b128 v189, v[138:141] offset:3456
	s_cbranch_vccnz .LBB0_1240
	s_andn2_b64 vcc, exec, s[54:55]
	s_ashr_i32 s57, s56, 31
	s_cbranch_vccnz .LBB0_1239
	s_lshl_b32 s79, s60, 19
	s_lshl_b64 s[60:61], s[56:57], 18
	s_add_u32 s90, s60, s79
	s_addc_u32 s91, s61, 0
	s_cmp_lg_u32 s86, 0
	s_cselect_b64 s[60:61], -1, 0
	s_lshl_b64 s[90:91], s[90:91], 1
	s_cmp_eq_u32 s86, 0
	v_lshl_add_u64 v[0:1], v[162:163], 0, s[90:91]
	v_lshl_add_u64 v[2:3], v[164:165], 0, s[90:91]
	s_cbranch_scc1 .LBB0_1236
	s_lshl_b32 s79, s86, 7
	s_add_u32 s90, s79, 0xffffc000
	s_addc_u32 s91, 0, -1
	v_lshl_add_u64 v[6:7], v[0:1], 0, s[90:91]
	v_lshl_add_u64 v[8:9], v[2:3], 0, s[90:91]
	global_load_dwordx4 v[84:87], v[6:7], off nt
	global_load_dwordx4 v[80:83], v[8:9], off nt
	s_andn2_b64 vcc, exec, s[60:61]
	s_cbranch_vccnz .LBB0_1237

	.amdhsa_kernel _Z8yoco_fwd4Args
		.amdhsa_group_segment_fixed_size 0
		.amdhsa_private_segment_fixed_size 0
		.amdhsa_kernarg_size 376
		.amdhsa_user_sgpr_count 2
		.amdhsa_user_sgpr_dispatch_ptr 0
		.amdhsa_user_sgpr_queue_ptr 0
		.amdhsa_user_sgpr_kernarg_segment_ptr 1
		.amdhsa_user_sgpr_dispatch_id 0
		.amdhsa_user_sgpr_kernarg_preload_length 0
		.amdhsa_user_sgpr_kernarg_preload_offset 0
		.amdhsa_user_sgpr_private_segment_size 0
		.amdhsa_uses_dynamic_stack 0
		.amdhsa_enable_private_segment 0
		.amdhsa_system_sgpr_workgroup_id_x 1
		.amdhsa_system_sgpr_workgroup_id_y 0
		.amdhsa_system_sgpr_workgroup_id_z 0
		.amdhsa_system_sgpr_workgroup_info 0
		.amdhsa_system_vgpr_workitem_id 2
		.amdhsa_next_free_vgpr 231
		.amdhsa_next_free_sgpr 100
		.amdhsa_accum_offset 232
		.amdhsa_reserve_vcc 1
		.amdhsa_float_round_mode_32 0
		.amdhsa_float_round_mode_16_64 0
		.amdhsa_float_denorm_mode_32 3
		.amdhsa_float_denorm_mode_16_64 3
		.amdhsa_dx10_clamp 1
		.amdhsa_ieee_mode 1
		.amdhsa_fp16_overflow 0
		.amdhsa_tg_split 0
		.amdhsa_exception_fp_ieee_invalid_op 0
		.amdhsa_exception_fp_denorm_src 0
		.amdhsa_exception_fp_ieee_div_zero 0
		.amdhsa_exception_fp_ieee_overflow 0
		.amdhsa_exception_fp_ieee_underflow 0
		.amdhsa_exception_fp_ieee_inexact 0
		.amdhsa_exception_int_div_zero 0
	.end_amdhsa_kernel

amdhsa.kernels:
  - .agpr_count:     0
    .args:
      - .offset:         0
        .size:           120
        .value_kind:     by_value
      - .offset:         120
        .size:           4
        .value_kind:     hidden_block_count_x
      - .offset:         124
        .size:           4
        .value_kind:     hidden_block_count_y
      - .offset:         128
        .size:           4
        .value_kind:     hidden_block_count_z
      - .offset:         132
        .size:           2
        .value_kind:     hidden_group_size_x
      - .offset:         134
        .size:           2
        .value_kind:     hidden_group_size_y
      - .offset:         136
        .size:           2
        .value_kind:     hidden_group_size_z
      - .offset:         138
        .size:           2
        .value_kind:     hidden_remainder_x
      - .offset:         140
        .size:           2
        .value_kind:     hidden_remainder_y
      - .offset:         142
        .size:           2
        .value_kind:     hidden_remainder_z
      - .offset:         160
        .size:           8
        .value_kind:     hidden_global_offset_x
      - .offset:         168
        .size:           8
        .value_kind:     hidden_global_offset_y
      - .offset:         176
        .size:           8
        .value_kind:     hidden_global_offset_z
      - .offset:         184
        .size:           2
        .value_kind:     hidden_grid_dims
      - .offset:         208
        .size:           8
        .value_kind:     hidden_multigrid_sync_arg
      - .offset:         240
        .size:           4
        .value_kind:     hidden_dynamic_lds_size
    .group_segment_fixed_size: 0
    .kernarg_segment_align: 8
    .kernarg_segment_size: 376
    .language:       OpenCL C
    .language_version:
      - 2
      - 0
    .max_flat_workgroup_size: 512
    .name:           _Z8yoco_fwd4Args
    .private_segment_fixed_size: 0
    .sgpr_count:     106
    .sgpr_spill_count: 3
    .symbol:         _Z8yoco_fwd4Args.kd
    .uniform_work_group_size: 1
    .uses_dynamic_stack: false
    .vgpr_count:     231
    .vgpr_spill_count: 0
    .wavefront_size: 64
